# speedup vs baseline: 1.0007x; 1.0007x over previous
.LBB0_169:
	ds_read_b128 v[66:69], v225
	ds_read_b128 v[70:73], v226
	ds_read_b128 v[74:77], v227
	ds_read_b128 v[78:81], v228
	ds_read_b128 v[212:215], v225 offset:8192
	ds_read_b128 v[250:253], v226 offset:8192
	s_add_i32 s8, s98, 0xffffff40
	s_cmp_le_i32 s8, s74
	s_waitcnt lgkmcnt(5)
	v_mfma_f32_32x32x16_bf16 v[82:97], v[66:69], v[98:101], 0
	s_waitcnt lgkmcnt(4)
	v_mfma_f32_32x32x16_bf16 v[82:97], v[70:73], v[102:105], v[82:97]
	s_waitcnt lgkmcnt(3)
	v_mfma_f32_32x32x16_bf16 v[82:97], v[74:77], v[106:109], v[82:97]
	s_waitcnt lgkmcnt(2)
	v_mfma_f32_32x32x16_bf16 v[82:97], v[78:81], v[110:113], v[82:97]
	s_waitcnt lgkmcnt(1)
	v_mfma_f32_32x32x16_bf16 v[66:81], v[212:215], v[98:101], 0
	ds_read_b128 v[212:215], v227 offset:8192
	s_waitcnt lgkmcnt(1)
	v_mfma_f32_32x32x16_bf16 v[66:81], v[250:253], v[102:105], v[66:81]
	ds_read_b128 v[250:253], v228 offset:8192
	s_waitcnt lgkmcnt(1)
	v_mfma_f32_32x32x16_bf16 v[66:81], v[212:215], v[106:109], v[66:81]
	s_waitcnt lgkmcnt(0)
	v_mfma_f32_32x32x16_bf16 v[66:81], v[250:253], v[110:113], v[66:81]
	s_cbranch_scc1 .LBB0_171
	v_cmp_gt_i32_e64 s[68:69], 26, v231
	v_cmp_gt_i32_e64 s[70:71], 27, v231
	v_cmp_gt_i32_e64 s[66:67], 25, v231
	s_and_b64 s[68:69], s[70:71], s[68:69]
	v_cmp_gt_i32_e64 s[64:65], 24, v231
	s_and_b64 s[66:67], s[68:69], s[66:67]
	v_cmp_gt_i32_e64 s[62:63], 19, v231
	s_and_b64 s[64:65], s[66:67], s[64:65]
	v_cmp_gt_i32_e64 s[60:61], 18, v231
	s_and_b64 s[62:63], s[64:65], s[62:63]
	v_cmp_gt_i32_e64 s[58:59], 17, v231
	s_and_b64 s[60:61], s[62:63], s[60:61]
	v_cmp_gt_i32_e64 s[56:57], 16, v231
	s_and_b64 s[58:59], s[60:61], s[58:59]
	v_cmp_gt_i32_e64 s[54:55], 11, v231
	s_and_b64 s[56:57], s[58:59], s[56:57]
	v_cmp_gt_i32_e64 s[52:53], 10, v231
	s_and_b64 s[54:55], s[56:57], s[54:55]
	v_cmp_gt_i32_e64 s[50:51], 9, v231
	s_and_b64 s[52:53], s[54:55], s[52:53]
	v_cmp_gt_i32_e64 s[48:49], 8, v231
	s_and_b64 s[50:51], s[52:53], s[50:51]
	v_cmp_gt_i32_e64 s[46:47], 3, v231
	s_and_b64 s[48:49], s[50:51], s[48:49]
	v_cmp_gt_i32_e64 s[44:45], 2, v231
	s_and_b64 s[46:47], s[48:49], s[46:47]
	v_cmp_gt_i32_e64 s[42:43], 1, v231
	s_and_b64 s[44:45], s[46:47], s[44:45]
	v_cmp_gt_i32_e64 s[40:41], 0, v231
	s_and_b64 s[42:43], s[44:45], s[42:43]
	s_and_b64 s[40:41], s[42:43], s[40:41]
	v_cmp_gt_i32_e64 s[36:37], 58, v231
	v_cndmask_b32_e64 v82, v82, v210, s[40:41]
	v_cmp_gt_i32_e64 s[40:41], 59, v231
	v_cmp_gt_i32_e64 s[34:35], 57, v231
	s_and_b64 s[36:37], s[40:41], s[36:37]
	v_cmp_gt_i32_e64 s[30:31], 56, v231
	s_and_b64 s[34:35], s[36:37], s[34:35]
	v_cmp_gt_i32_e64 s[28:29], 51, v231
	s_and_b64 s[30:31], s[34:35], s[30:31]
	v_cmp_gt_i32_e64 s[26:27], 50, v231
	s_and_b64 s[28:29], s[30:31], s[28:29]
	v_cmp_gt_i32_e64 s[24:25], 49, v231
	s_and_b64 s[26:27], s[28:29], s[26:27]
	v_cmp_gt_i32_e64 s[22:23], 48, v231
	s_and_b64 s[24:25], s[26:27], s[24:25]
	v_cmp_gt_i32_e64 s[20:21], 43, v231
	s_and_b64 s[22:23], s[24:25], s[22:23]
	v_cmp_gt_i32_e64 s[18:19], 42, v231
	s_and_b64 s[20:21], s[22:23], s[20:21]
	v_cmp_gt_i32_e64 s[16:17], 41, v231
	s_and_b64 s[18:19], s[20:21], s[18:19]
	v_cmp_gt_i32_e64 s[14:15], 40, v231
	s_and_b64 s[16:17], s[18:19], s[16:17]
	v_cmp_gt_i32_e64 s[12:13], 35, v231
	s_and_b64 s[14:15], s[16:17], s[14:15]
	v_cmp_gt_i32_e64 s[10:11], 34, v231
	s_and_b64 s[12:13], s[14:15], s[12:13]
	v_cmp_gt_i32_e64 s[8:9], 33, v231
	s_and_b64 s[10:11], s[12:13], s[10:11]
	v_cmp_gt_i32_e32 vcc, 32, v231
	s_and_b64 s[8:9], s[10:11], s[8:9]
	s_and_b64 vcc, s[8:9], vcc
	v_cndmask_b32_e64 v97, v97, v210, s[70:71]
	v_cndmask_b32_e64 v96, v96, v210, s[68:69]
	v_cndmask_b32_e64 v95, v95, v210, s[66:67]
	v_cndmask_b32_e64 v94, v94, v210, s[64:65]
	v_cndmask_b32_e64 v93, v93, v210, s[62:63]
	v_cndmask_b32_e64 v92, v92, v210, s[60:61]
	v_cndmask_b32_e64 v91, v91, v210, s[58:59]
	v_cndmask_b32_e64 v90, v90, v210, s[56:57]
	v_cndmask_b32_e64 v89, v89, v210, s[54:55]
	v_cndmask_b32_e64 v88, v88, v210, s[52:53]
	v_cndmask_b32_e64 v87, v87, v210, s[50:51]
	v_cndmask_b32_e64 v86, v86, v210, s[48:49]
	v_cndmask_b32_e64 v85, v85, v210, s[46:47]
	v_cndmask_b32_e64 v84, v84, v210, s[44:45]
	v_cndmask_b32_e64 v83, v83, v210, s[42:43]
	v_cndmask_b32_e64 v81, v81, v210, s[40:41]
	v_cndmask_b32_e64 v80, v80, v210, s[36:37]
	v_cndmask_b32_e64 v79, v79, v210, s[34:35]
	v_cndmask_b32_e64 v78, v78, v210, s[30:31]
	v_cndmask_b32_e64 v77, v77, v210, s[28:29]
	v_cndmask_b32_e64 v76, v76, v210, s[26:27]
	v_cndmask_b32_e64 v75, v75, v210, s[24:25]
	v_cndmask_b32_e64 v74, v74, v210, s[22:23]
	v_cndmask_b32_e64 v73, v73, v210, s[20:21]
	v_cndmask_b32_e64 v72, v72, v210, s[18:19]
	v_cndmask_b32_e64 v71, v71, v210, s[16:17]
	v_cndmask_b32_e64 v70, v70, v210, s[14:15]
	v_cndmask_b32_e64 v69, v69, v210, s[12:13]
	v_cndmask_b32_e64 v68, v68, v210, s[10:11]
	v_cndmask_b32_e64 v67, v67, v210, s[8:9]
	v_cndmask_b32_e32 v66, v66, v210, vcc

.LBB0_175:
	v_cndmask_b32_e64 v233, v234, v233, s[8:9]
	v_mul_f32_e32 v206, 0xbe38aa3b, v233
	v_fmamk_f32 v82, v82, 0x3e38aa3b, v206
	v_fmamk_f32 v83, v83, 0x3e38aa3b, v206
	v_fmamk_f32 v84, v84, 0x3e38aa3b, v206
	v_fmamk_f32 v85, v85, 0x3e38aa3b, v206
	v_fmamk_f32 v86, v86, 0x3e38aa3b, v206
	v_fmamk_f32 v87, v87, 0x3e38aa3b, v206
	v_fmamk_f32 v88, v88, 0x3e38aa3b, v206
	v_fmamk_f32 v89, v89, 0x3e38aa3b, v206
	v_fmamk_f32 v90, v90, 0x3e38aa3b, v206
	v_fmamk_f32 v91, v91, 0x3e38aa3b, v206
	v_fmamk_f32 v92, v92, 0x3e38aa3b, v206
	v_fmamk_f32 v93, v93, 0x3e38aa3b, v206
	v_fmamk_f32 v94, v94, 0x3e38aa3b, v206
	v_fmamk_f32 v95, v95, 0x3e38aa3b, v206
	v_fmamk_f32 v96, v96, 0x3e38aa3b, v206
	v_fmamk_f32 v97, v97, 0x3e38aa3b, v206
	v_fmamk_f32 v66, v66, 0x3e38aa3b, v206
	v_fmamk_f32 v67, v67, 0x3e38aa3b, v206
	v_fmamk_f32 v68, v68, 0x3e38aa3b, v206
	v_fmamk_f32 v69, v69, 0x3e38aa3b, v206
	v_fmamk_f32 v70, v70, 0x3e38aa3b, v206
	v_fmamk_f32 v71, v71, 0x3e38aa3b, v206
	v_fmamk_f32 v72, v72, 0x3e38aa3b, v206
	v_fmamk_f32 v73, v73, 0x3e38aa3b, v206
	v_fmamk_f32 v74, v74, 0x3e38aa3b, v206
	v_fmamk_f32 v75, v75, 0x3e38aa3b, v206
	v_fmamk_f32 v76, v76, 0x3e38aa3b, v206
	v_fmamk_f32 v77, v77, 0x3e38aa3b, v206
	v_fmamk_f32 v78, v78, 0x3e38aa3b, v206
	v_fmamk_f32 v79, v79, 0x3e38aa3b, v206
	v_fmamk_f32 v80, v80, 0x3e38aa3b, v206
	v_fmac_f32_e32 v206, 0x3e38aa3b, v81
	v_exp_f32_e32 v81, v82
	v_exp_f32_e32 v82, v83
	v_exp_f32_e32 v83, v84
	v_exp_f32_e32 v84, v85
	v_exp_f32_e32 v85, v86
	v_exp_f32_e32 v86, v87
	v_exp_f32_e32 v87, v88
	v_exp_f32_e32 v88, v89
	v_exp_f32_e32 v89, v90
	v_exp_f32_e32 v90, v91
	v_exp_f32_e32 v91, v92
	v_exp_f32_e32 v92, v93
	v_exp_f32_e32 v93, v94
	v_exp_f32_e32 v94, v95
	v_exp_f32_e32 v95, v96
	v_exp_f32_e32 v96, v97
	v_exp_f32_e32 v97, v66
	v_add_f32_e32 v66, 0, v81
	v_add_f32_e32 v66, v82, v66
	v_add_f32_e32 v66, v83, v66
	v_add_f32_e32 v66, v84, v66
	v_add_f32_e32 v66, v85, v66
	v_add_f32_e32 v66, v86, v66
	v_add_f32_e32 v66, v87, v66
	v_add_f32_e32 v66, v88, v66
	v_add_f32_e32 v66, v89, v66
	v_add_f32_e32 v66, v90, v66
	v_add_f32_e32 v66, v91, v66
	v_add_f32_e32 v66, v92, v66
	v_add_f32_e32 v66, v93, v66
	v_exp_f32_e32 v212, v67
	v_add_f32_e32 v66, v94, v66
	v_exp_f32_e32 v213, v68
	v_add_f32_e32 v66, v95, v66
	v_exp_f32_e32 v214, v69
	v_add_f32_e32 v66, v96, v66
	v_exp_f32_e32 v215, v70
	v_add_f32_e32 v66, v97, v66
	v_exp_f32_e32 v236, v71
	v_add_f32_e32 v66, v212, v66
	v_exp_f32_e32 v237, v72
	v_add_f32_e32 v66, v213, v66
	v_exp_f32_e32 v238, v73
	v_add_f32_e32 v66, v214, v66
	v_exp_f32_e32 v239, v74
	v_add_f32_e32 v66, v215, v66
	v_exp_f32_e32 v240, v75
	v_add_f32_e32 v66, v236, v66
	v_exp_f32_e32 v241, v76
	v_add_f32_e32 v66, v237, v66
	v_exp_f32_e32 v242, v77
	v_add_f32_e32 v66, v238, v66
	v_exp_f32_e32 v243, v78
	v_add_f32_e32 v66, v239, v66
	v_exp_f32_e32 v244, v79
	v_add_f32_e32 v66, v240, v66
	v_exp_f32_e32 v245, v80
	v_add_f32_e32 v66, v241, v66
	v_exp_f32_e32 v206, v206
	v_add_f32_e32 v66, v242, v66
	v_add_f32_e32 v66, v243, v66
	v_add_f32_e32 v66, v244, v66
	v_add_f32_e32 v66, v245, v66
	v_add_f32_e32 v234, v206, v66
	v_mov_b32_e32 v235, v234
	s_nop 1
	v_permlane32_swap_b32_e32 v234, v235
	v_cvt_pk_bf16_f32 v66, v81, v82
	v_cvt_pk_bf16_f32 v67, v83, v84
	v_cvt_pk_bf16_f32 v68, v85, v86
	v_cvt_pk_bf16_f32 v69, v87, v88
	v_cvt_pk_bf16_f32 v70, v89, v90
	v_cvt_pk_bf16_f32 v71, v91, v92
	v_cvt_pk_bf16_f32 v72, v93, v94
	v_cvt_pk_bf16_f32 v73, v95, v96
	v_cvt_pk_bf16_f32 v74, v97, v212
	v_cvt_pk_bf16_f32 v75, v213, v214
	v_cvt_pk_bf16_f32 v76, v215, v236
	v_cvt_pk_bf16_f32 v77, v237, v238
	v_cvt_pk_bf16_f32 v78, v239, v240
	v_cvt_pk_bf16_f32 v79, v241, v242
	v_cvt_pk_bf16_f32 v80, v243, v244
	v_cvt_pk_bf16_f32 v81, v245, v206
	s_nop 0
	v_permlane32_swap_b32_e32 v66, v68
	v_permlane32_swap_b32_e32 v67, v69
	v_permlane32_swap_b32_e32 v70, v72
	v_permlane32_swap_b32_e32 v71, v73
	v_permlane32_swap_b32_e32 v74, v76
	v_permlane32_swap_b32_e32 v75, v77
	v_permlane32_swap_b32_e32 v78, v80
	v_permlane32_swap_b32_e32 v79, v81
	ds_read_b64_tr_b16 v[82:83], v153 offset:0
	ds_read_b64_tr_b16 v[84:85], v153 offset:0x800
	ds_read_b64_tr_b16 v[86:87], v153 offset:0x1000
	ds_read_b64_tr_b16 v[88:89], v153 offset:0x1800
	ds_read_b64_tr_b16 v[90:91], v153 offset:0x2000
	ds_read_b64_tr_b16 v[92:93], v153 offset:0x2800
	ds_read_b64_tr_b16 v[94:95], v153 offset:0x3000
	ds_read_b64_tr_b16 v[96:97], v153 offset:0x3800
	s_nop 0
	s_waitcnt lgkmcnt(6)
	v_mfma_f32_32x32x16_bf16 v[50:65], v[66:69], v[82:85], v[50:65]
	ds_read_b64_tr_b16 v[82:83], v153 offset:0x200
	ds_read_b64_tr_b16 v[84:85], v153 offset:0xa00
	s_waitcnt lgkmcnt(6)
	v_mfma_f32_32x32x16_bf16 v[50:65], v[70:73], v[86:89], v[50:65]
	ds_read_b64_tr_b16 v[86:87], v153 offset:0x1200
	ds_read_b64_tr_b16 v[88:89], v153 offset:0x1a00
	s_waitcnt lgkmcnt(6)
	v_mfma_f32_32x32x16_bf16 v[50:65], v[74:77], v[90:93], v[50:65]
	ds_read_b64_tr_b16 v[90:91], v153 offset:0x2200
	ds_read_b64_tr_b16 v[92:93], v153 offset:0x2a00
	s_waitcnt lgkmcnt(6)
	v_mfma_f32_32x32x16_bf16 v[50:65], v[78:81], v[94:97], v[50:65]
	ds_read_b64_tr_b16 v[94:95], v153 offset:0x3200
	ds_read_b64_tr_b16 v[96:97], v153 offset:0x3a00
	s_waitcnt lgkmcnt(6)
	v_mfma_f32_32x32x16_bf16 v[34:49], v[66:69], v[82:85], v[34:49]
	ds_read_b64_tr_b16 v[82:83], v153 offset:0x400
	ds_read_b64_tr_b16 v[84:85], v153 offset:0xc00
	s_waitcnt lgkmcnt(6)
	v_mfma_f32_32x32x16_bf16 v[34:49], v[70:73], v[86:89], v[34:49]
	ds_read_b64_tr_b16 v[86:87], v153 offset:0x1400
	ds_read_b64_tr_b16 v[88:89], v153 offset:0x1c00
	s_waitcnt lgkmcnt(6)
	v_mfma_f32_32x32x16_bf16 v[34:49], v[74:77], v[90:93], v[34:49]
	ds_read_b64_tr_b16 v[90:91], v153 offset:0x2400
	ds_read_b64_tr_b16 v[92:93], v153 offset:0x2c00
	s_waitcnt lgkmcnt(6)
	v_mfma_f32_32x32x16_bf16 v[34:49], v[78:81], v[94:97], v[34:49]
	ds_read_b64_tr_b16 v[94:95], v153 offset:0x3400
	ds_read_b64_tr_b16 v[96:97], v153 offset:0x3c00
	s_waitcnt lgkmcnt(6)
	v_mfma_f32_32x32x16_bf16 v[18:33], v[66:69], v[82:85], v[18:33]
	ds_read_b64_tr_b16 v[82:83], v153 offset:0x600
	ds_read_b64_tr_b16 v[84:85], v153 offset:0xe00
	s_waitcnt lgkmcnt(6)
	v_mfma_f32_32x32x16_bf16 v[18:33], v[70:73], v[86:89], v[18:33]
	ds_read_b64_tr_b16 v[86:87], v153 offset:0x1600
	ds_read_b64_tr_b16 v[88:89], v153 offset:0x1e00
	s_waitcnt lgkmcnt(6)
	v_mfma_f32_32x32x16_bf16 v[18:33], v[74:77], v[90:93], v[18:33]
	ds_read_b64_tr_b16 v[90:91], v153 offset:0x2600
	ds_read_b64_tr_b16 v[92:93], v153 offset:0x2e00
	s_waitcnt lgkmcnt(6)
	v_mfma_f32_32x32x16_bf16 v[18:33], v[78:81], v[94:97], v[18:33]
	ds_read_b64_tr_b16 v[94:95], v153 offset:0x3600
	ds_read_b64_tr_b16 v[96:97], v153 offset:0x3e00
	s_waitcnt lgkmcnt(6)
	v_mfma_f32_32x32x16_bf16 v[2:17], v[66:69], v[82:85], v[2:17]
	s_andn2_b64 vcc, exec, s[72:73]
	s_waitcnt lgkmcnt(4)
	v_mfma_f32_32x32x16_bf16 v[2:17], v[70:73], v[86:89], v[2:17]
	s_waitcnt lgkmcnt(2)
	v_mfma_f32_32x32x16_bf16 v[2:17], v[74:77], v[90:93], v[2:17]
	s_waitcnt lgkmcnt(0)
	v_mfma_f32_32x32x16_bf16 v[2:17], v[78:81], v[94:97], v[2:17]
	s_cbranch_vccnz .LBB0_177
	v_add_u32_e32 v66, s88, v157
	s_waitcnt vmcnt(3)
	ds_write_b128 v224, v[114:117] offset:49152
	s_waitcnt vmcnt(1)
	ds_write_b128 v224, v[122:125] offset:57344
	ds_write_b128 v66, v[118:121]
	v_add_u32_e32 v66, s88, v155
	s_waitcnt vmcnt(0)
	ds_write_b128 v66, v[126:129]

.LBB0_179:
	ds_read_b128 v[66:69], v225 offset:16384
	ds_read_b128 v[70:73], v226 offset:16384
	ds_read_b128 v[74:77], v227 offset:16384
	ds_read_b128 v[78:81], v228 offset:16384
	ds_read_b128 v[212:215], v225 offset:24576
	ds_read_b128 v[250:253], v226 offset:24576
	s_add_i32 s8, s98, 0xffffff80
	s_cmp_le_i32 s8, s74
	s_waitcnt lgkmcnt(5)
	v_mfma_f32_32x32x16_bf16 v[82:97], v[66:69], v[98:101], 0
	s_waitcnt lgkmcnt(4)
	v_mfma_f32_32x32x16_bf16 v[82:97], v[70:73], v[102:105], v[82:97]
	s_waitcnt lgkmcnt(3)
	v_mfma_f32_32x32x16_bf16 v[82:97], v[74:77], v[106:109], v[82:97]
	s_waitcnt lgkmcnt(2)
	v_mfma_f32_32x32x16_bf16 v[82:97], v[78:81], v[110:113], v[82:97]
	s_waitcnt lgkmcnt(1)
	v_mfma_f32_32x32x16_bf16 v[66:81], v[212:215], v[98:101], 0
	ds_read_b128 v[212:215], v227 offset:24576
	s_waitcnt lgkmcnt(1)
	v_mfma_f32_32x32x16_bf16 v[66:81], v[250:253], v[102:105], v[66:81]
	ds_read_b128 v[250:253], v228 offset:24576
	s_waitcnt lgkmcnt(1)
	v_mfma_f32_32x32x16_bf16 v[66:81], v[212:215], v[106:109], v[66:81]
	s_waitcnt lgkmcnt(0)
	v_mfma_f32_32x32x16_bf16 v[66:81], v[250:253], v[110:113], v[66:81]
	s_cbranch_scc1 .LBB0_181
	v_subrev_u32_e32 v206, 64, v231
	v_cmp_gt_i32_e64 s[68:69], 26, v206
	v_cmp_gt_i32_e64 s[70:71], 27, v206
	v_cmp_gt_i32_e64 s[66:67], 25, v206
	s_and_b64 s[68:69], s[70:71], s[68:69]
	v_cmp_gt_i32_e64 s[64:65], 24, v206
	s_and_b64 s[66:67], s[68:69], s[66:67]
	v_cmp_gt_i32_e64 s[62:63], 19, v206
	s_and_b64 s[64:65], s[66:67], s[64:65]
	v_cmp_gt_i32_e64 s[60:61], 18, v206
	s_and_b64 s[62:63], s[64:65], s[62:63]
	v_cmp_gt_i32_e64 s[58:59], 17, v206
	s_and_b64 s[60:61], s[62:63], s[60:61]
	v_cmp_gt_i32_e64 s[56:57], 16, v206
	s_and_b64 s[58:59], s[60:61], s[58:59]
	v_cmp_gt_i32_e64 s[54:55], 11, v206
	s_and_b64 s[56:57], s[58:59], s[56:57]
	v_cmp_gt_i32_e64 s[52:53], 10, v206
	s_and_b64 s[54:55], s[56:57], s[54:55]
	v_cmp_gt_i32_e64 s[50:51], 9, v206
	s_and_b64 s[52:53], s[54:55], s[52:53]
	v_cmp_gt_i32_e64 s[48:49], 8, v206
	s_and_b64 s[50:51], s[52:53], s[50:51]
	v_cmp_gt_i32_e64 s[46:47], 3, v206
	s_and_b64 s[48:49], s[50:51], s[48:49]
	v_cmp_gt_i32_e64 s[44:45], 2, v206
	s_and_b64 s[46:47], s[48:49], s[46:47]
	v_cmp_gt_i32_e64 s[42:43], 1, v206
	s_and_b64 s[44:45], s[46:47], s[44:45]
	v_cmp_gt_i32_e64 s[40:41], 0, v206
	s_and_b64 s[42:43], s[44:45], s[42:43]
	s_and_b64 s[40:41], s[42:43], s[40:41]
	v_cmp_gt_i32_e64 s[36:37], 58, v206
	v_cndmask_b32_e64 v82, v82, v210, s[40:41]
	v_cmp_gt_i32_e64 s[40:41], 59, v206
	v_cmp_gt_i32_e64 s[34:35], 57, v206
	s_and_b64 s[36:37], s[40:41], s[36:37]
	v_cmp_gt_i32_e64 s[30:31], 56, v206
	s_and_b64 s[34:35], s[36:37], s[34:35]
	v_cmp_gt_i32_e64 s[28:29], 51, v206
	s_and_b64 s[30:31], s[34:35], s[30:31]
	v_cmp_gt_i32_e64 s[26:27], 50, v206
	s_and_b64 s[28:29], s[30:31], s[28:29]
	v_cmp_gt_i32_e64 s[24:25], 49, v206
	s_and_b64 s[26:27], s[28:29], s[26:27]
	v_cmp_gt_i32_e64 s[22:23], 48, v206
	s_and_b64 s[24:25], s[26:27], s[24:25]
	v_cmp_gt_i32_e64 s[20:21], 43, v206
	s_and_b64 s[22:23], s[24:25], s[22:23]
	v_cmp_gt_i32_e64 s[18:19], 42, v206
	s_and_b64 s[20:21], s[22:23], s[20:21]
	v_cmp_gt_i32_e64 s[16:17], 41, v206
	s_and_b64 s[18:19], s[20:21], s[18:19]
	v_cmp_gt_i32_e64 s[14:15], 40, v206
	s_and_b64 s[16:17], s[18:19], s[16:17]
	v_cmp_gt_i32_e64 s[12:13], 35, v206
	s_and_b64 s[14:15], s[16:17], s[14:15]
	v_cmp_gt_i32_e64 s[10:11], 34, v206
	s_and_b64 s[12:13], s[14:15], s[12:13]
	v_cmp_gt_i32_e64 s[8:9], 33, v206
	s_and_b64 s[10:11], s[12:13], s[10:11]
	v_cmp_gt_i32_e32 vcc, 32, v206
	s_and_b64 s[8:9], s[10:11], s[8:9]
	s_and_b64 vcc, s[8:9], vcc
	v_cndmask_b32_e64 v97, v97, v210, s[70:71]
	v_cndmask_b32_e64 v96, v96, v210, s[68:69]
	v_cndmask_b32_e64 v95, v95, v210, s[66:67]
	v_cndmask_b32_e64 v94, v94, v210, s[64:65]
	v_cndmask_b32_e64 v93, v93, v210, s[62:63]
	v_cndmask_b32_e64 v92, v92, v210, s[60:61]
	v_cndmask_b32_e64 v91, v91, v210, s[58:59]
	v_cndmask_b32_e64 v90, v90, v210, s[56:57]
	v_cndmask_b32_e64 v89, v89, v210, s[54:55]
	v_cndmask_b32_e64 v88, v88, v210, s[52:53]
	v_cndmask_b32_e64 v87, v87, v210, s[50:51]
	v_cndmask_b32_e64 v86, v86, v210, s[48:49]
	v_cndmask_b32_e64 v85, v85, v210, s[46:47]
	v_cndmask_b32_e64 v84, v84, v210, s[44:45]
	v_cndmask_b32_e64 v83, v83, v210, s[42:43]
	v_cndmask_b32_e64 v81, v81, v210, s[40:41]
	v_cndmask_b32_e64 v80, v80, v210, s[36:37]
	v_cndmask_b32_e64 v79, v79, v210, s[34:35]
	v_cndmask_b32_e64 v78, v78, v210, s[30:31]
	v_cndmask_b32_e64 v77, v77, v210, s[28:29]
	v_cndmask_b32_e64 v76, v76, v210, s[26:27]
	v_cndmask_b32_e64 v75, v75, v210, s[24:25]
	v_cndmask_b32_e64 v74, v74, v210, s[22:23]
	v_cndmask_b32_e64 v73, v73, v210, s[20:21]
	v_cndmask_b32_e64 v72, v72, v210, s[18:19]
	v_cndmask_b32_e64 v71, v71, v210, s[16:17]
	v_cndmask_b32_e64 v70, v70, v210, s[14:15]
	v_cndmask_b32_e64 v69, v69, v210, s[12:13]
	v_cndmask_b32_e64 v68, v68, v210, s[10:11]
	v_cndmask_b32_e64 v67, v67, v210, s[8:9]
	v_cndmask_b32_e32 v66, v66, v210, vcc

.LBB0_185:
	v_cndmask_b32_e64 v233, v237, v233, s[8:9]
	v_mul_f32_e32 v206, 0xbe38aa3b, v233
	v_fmamk_f32 v82, v82, 0x3e38aa3b, v206
	v_fmamk_f32 v83, v83, 0x3e38aa3b, v206
	v_fmamk_f32 v84, v84, 0x3e38aa3b, v206
	v_fmamk_f32 v85, v85, 0x3e38aa3b, v206
	v_fmamk_f32 v86, v86, 0x3e38aa3b, v206
	v_fmamk_f32 v87, v87, 0x3e38aa3b, v206
	v_fmamk_f32 v88, v88, 0x3e38aa3b, v206
	v_fmamk_f32 v89, v89, 0x3e38aa3b, v206
	v_fmamk_f32 v90, v90, 0x3e38aa3b, v206
	v_fmamk_f32 v91, v91, 0x3e38aa3b, v206
	v_fmamk_f32 v92, v92, 0x3e38aa3b, v206
	v_fmamk_f32 v93, v93, 0x3e38aa3b, v206
	v_fmamk_f32 v94, v94, 0x3e38aa3b, v206
	v_fmamk_f32 v95, v95, 0x3e38aa3b, v206
	v_fmamk_f32 v96, v96, 0x3e38aa3b, v206
	v_fmamk_f32 v97, v97, 0x3e38aa3b, v206
	v_fmamk_f32 v66, v66, 0x3e38aa3b, v206
	v_fmamk_f32 v67, v67, 0x3e38aa3b, v206
	v_fmamk_f32 v68, v68, 0x3e38aa3b, v206
	v_fmamk_f32 v69, v69, 0x3e38aa3b, v206
	v_fmamk_f32 v70, v70, 0x3e38aa3b, v206
	v_fmamk_f32 v71, v71, 0x3e38aa3b, v206
	v_fmamk_f32 v72, v72, 0x3e38aa3b, v206
	v_fmamk_f32 v73, v73, 0x3e38aa3b, v206
	v_fmamk_f32 v74, v74, 0x3e38aa3b, v206
	v_fmamk_f32 v75, v75, 0x3e38aa3b, v206
	v_fmamk_f32 v76, v76, 0x3e38aa3b, v206
	v_fmamk_f32 v77, v77, 0x3e38aa3b, v206
	v_fmamk_f32 v78, v78, 0x3e38aa3b, v206
	v_fmamk_f32 v79, v79, 0x3e38aa3b, v206
	v_fmamk_f32 v80, v80, 0x3e38aa3b, v206
	v_fmac_f32_e32 v206, 0x3e38aa3b, v81
	v_exp_f32_e32 v81, v82
	v_exp_f32_e32 v82, v83
	v_exp_f32_e32 v83, v84
	v_exp_f32_e32 v84, v85
	v_exp_f32_e32 v85, v86
	v_exp_f32_e32 v86, v87
	v_exp_f32_e32 v87, v88
	v_exp_f32_e32 v88, v89
	v_exp_f32_e32 v89, v90
	v_exp_f32_e32 v90, v91
	v_exp_f32_e32 v91, v92
	v_exp_f32_e32 v92, v93
	v_exp_f32_e32 v93, v94
	v_exp_f32_e32 v94, v95
	v_exp_f32_e32 v95, v96
	v_exp_f32_e32 v96, v97
	v_add_f32_e32 v97, v234, v235
	v_fmac_f32_e32 v97, v232, v1
	v_exp_f32_e32 v1, v66
	v_add_f32_e32 v66, 0, v81
	v_add_f32_e32 v66, v82, v66
	v_add_f32_e32 v66, v83, v66
	v_add_f32_e32 v66, v84, v66
	v_add_f32_e32 v66, v85, v66
	v_add_f32_e32 v66, v86, v66
	v_add_f32_e32 v66, v87, v66
	v_add_f32_e32 v66, v88, v66
	v_add_f32_e32 v66, v89, v66
	v_add_f32_e32 v66, v90, v66
	v_add_f32_e32 v66, v91, v66
	v_add_f32_e32 v66, v92, v66
	v_add_f32_e32 v66, v93, v66
	v_exp_f32_e32 v212, v67
	v_add_f32_e32 v66, v94, v66
	v_exp_f32_e32 v213, v68
	v_add_f32_e32 v66, v95, v66
	v_exp_f32_e32 v214, v69
	v_add_f32_e32 v66, v96, v66
	v_exp_f32_e32 v215, v70
	v_add_f32_e32 v66, v1, v66
	v_exp_f32_e32 v234, v71
	v_add_f32_e32 v66, v212, v66
	v_exp_f32_e32 v235, v72
	v_add_f32_e32 v66, v213, v66
	v_exp_f32_e32 v237, v73
	v_add_f32_e32 v66, v214, v66
	v_exp_f32_e32 v238, v74
	v_add_f32_e32 v66, v215, v66
	v_exp_f32_e32 v239, v75
	v_add_f32_e32 v66, v234, v66
	v_exp_f32_e32 v240, v76
	v_add_f32_e32 v66, v235, v66
	v_exp_f32_e32 v241, v77
	v_add_f32_e32 v66, v237, v66
	v_exp_f32_e32 v242, v78
	v_add_f32_e32 v66, v238, v66
	v_exp_f32_e32 v243, v79
	v_add_f32_e32 v66, v239, v66
	v_exp_f32_e32 v244, v80
	v_add_f32_e32 v66, v240, v66
	v_exp_f32_e32 v206, v206
	v_add_f32_e32 v66, v241, v66
	v_add_f32_e32 v66, v242, v66
	v_add_f32_e32 v66, v243, v66
	v_add_f32_e32 v66, v244, v66
	v_add_f32_e32 v66, v206, v66
	v_mov_b32_e32 v67, v66
	s_nop 1
	v_permlane32_swap_b32_e32 v66, v67
	v_add_f32_e32 v232, v66, v67
	v_fmac_f32_e32 v232, v97, v236
	v_cvt_pk_bf16_f32 v66, v81, v82
	v_cvt_pk_bf16_f32 v67, v83, v84
	v_cvt_pk_bf16_f32 v68, v85, v86
	v_cvt_pk_bf16_f32 v69, v87, v88
	v_cvt_pk_bf16_f32 v70, v89, v90
	v_cvt_pk_bf16_f32 v71, v91, v92
	v_cvt_pk_bf16_f32 v72, v93, v94
	v_cvt_pk_bf16_f32 v73, v95, v96
	v_cvt_pk_bf16_f32 v74, v1, v212
	v_cvt_pk_bf16_f32 v75, v213, v214
	v_cvt_pk_bf16_f32 v76, v215, v234
	v_cvt_pk_bf16_f32 v77, v235, v237
	v_cvt_pk_bf16_f32 v78, v238, v239
	v_cvt_pk_bf16_f32 v79, v240, v241
	v_cvt_pk_bf16_f32 v80, v242, v243
	v_cvt_pk_bf16_f32 v81, v244, v206
	s_nop 0
	v_permlane32_swap_b32_e32 v66, v68
	v_permlane32_swap_b32_e32 v67, v69
	v_permlane32_swap_b32_e32 v70, v72
	v_permlane32_swap_b32_e32 v71, v73
	v_permlane32_swap_b32_e32 v74, v76
	v_permlane32_swap_b32_e32 v75, v77
	v_permlane32_swap_b32_e32 v78, v80
	v_permlane32_swap_b32_e32 v79, v81
	ds_read_b64_tr_b16 v[82:83], v153 offset:0x4000
	ds_read_b64_tr_b16 v[84:85], v153 offset:0x4800
	ds_read_b64_tr_b16 v[86:87], v153 offset:0x5000
	ds_read_b64_tr_b16 v[88:89], v153 offset:0x5800
	ds_read_b64_tr_b16 v[90:91], v153 offset:0x6000
	ds_read_b64_tr_b16 v[92:93], v153 offset:0x6800
	ds_read_b64_tr_b16 v[94:95], v153 offset:0x7000
	ds_read_b64_tr_b16 v[96:97], v153 offset:0x7800
	s_nop 0
	s_waitcnt lgkmcnt(6)
	v_mfma_f32_32x32x16_bf16 v[50:65], v[66:69], v[82:85], v[50:65]
	ds_read_b64_tr_b16 v[82:83], v153 offset:0x4200
	ds_read_b64_tr_b16 v[84:85], v153 offset:0x4a00
	s_waitcnt lgkmcnt(6)
	v_mfma_f32_32x32x16_bf16 v[50:65], v[70:73], v[86:89], v[50:65]
	ds_read_b64_tr_b16 v[86:87], v153 offset:0x5200
	ds_read_b64_tr_b16 v[88:89], v153 offset:0x5a00
	s_waitcnt lgkmcnt(6)
	v_mfma_f32_32x32x16_bf16 v[50:65], v[74:77], v[90:93], v[50:65]
	ds_read_b64_tr_b16 v[90:91], v153 offset:0x6200
	ds_read_b64_tr_b16 v[92:93], v153 offset:0x6a00
	s_waitcnt lgkmcnt(6)
	v_mfma_f32_32x32x16_bf16 v[50:65], v[78:81], v[94:97], v[50:65]
	ds_read_b64_tr_b16 v[94:95], v153 offset:0x7200
	ds_read_b64_tr_b16 v[96:97], v153 offset:0x7a00
	s_waitcnt lgkmcnt(6)
	v_mfma_f32_32x32x16_bf16 v[34:49], v[66:69], v[82:85], v[34:49]
	ds_read_b64_tr_b16 v[82:83], v153 offset:0x4400
	ds_read_b64_tr_b16 v[84:85], v153 offset:0x4c00
	s_waitcnt lgkmcnt(6)
	v_mfma_f32_32x32x16_bf16 v[34:49], v[70:73], v[86:89], v[34:49]
	ds_read_b64_tr_b16 v[86:87], v153 offset:0x5400
	ds_read_b64_tr_b16 v[88:89], v153 offset:0x5c00
	s_waitcnt lgkmcnt(6)
	v_mfma_f32_32x32x16_bf16 v[34:49], v[74:77], v[90:93], v[34:49]
	ds_read_b64_tr_b16 v[90:91], v153 offset:0x6400
	ds_read_b64_tr_b16 v[92:93], v153 offset:0x6c00
	s_waitcnt lgkmcnt(6)
	v_mfma_f32_32x32x16_bf16 v[34:49], v[78:81], v[94:97], v[34:49]
	ds_read_b64_tr_b16 v[94:95], v153 offset:0x7400
	ds_read_b64_tr_b16 v[96:97], v153 offset:0x7c00
	s_waitcnt lgkmcnt(6)
	v_mfma_f32_32x32x16_bf16 v[18:33], v[66:69], v[82:85], v[18:33]
	ds_read_b64_tr_b16 v[82:83], v153 offset:0x4600
	ds_read_b64_tr_b16 v[84:85], v153 offset:0x4e00
	s_waitcnt lgkmcnt(6)
	v_mfma_f32_32x32x16_bf16 v[18:33], v[70:73], v[86:89], v[18:33]
	ds_read_b64_tr_b16 v[86:87], v153 offset:0x5600
	ds_read_b64_tr_b16 v[88:89], v153 offset:0x5e00
	s_waitcnt lgkmcnt(6)
	v_mfma_f32_32x32x16_bf16 v[18:33], v[74:77], v[90:93], v[18:33]
	ds_read_b64_tr_b16 v[90:91], v153 offset:0x6600
	ds_read_b64_tr_b16 v[92:93], v153 offset:0x6e00
	s_waitcnt lgkmcnt(6)
	v_mfma_f32_32x32x16_bf16 v[18:33], v[78:81], v[94:97], v[18:33]
	ds_read_b64_tr_b16 v[94:95], v153 offset:0x7600
	ds_read_b64_tr_b16 v[96:97], v153 offset:0x7e00
	s_waitcnt lgkmcnt(6)
	v_mfma_f32_32x32x16_bf16 v[2:17], v[66:69], v[82:85], v[2:17]
	s_andn2_b64 vcc, exec, s[38:39]
	s_waitcnt lgkmcnt(0)
	s_barrier
	s_waitcnt lgkmcnt(4)
	v_mfma_f32_32x32x16_bf16 v[2:17], v[70:73], v[86:89], v[2:17]
	s_waitcnt lgkmcnt(2)
	v_mfma_f32_32x32x16_bf16 v[2:17], v[74:77], v[90:93], v[2:17]
	s_waitcnt lgkmcnt(0)
	v_mfma_f32_32x32x16_bf16 v[2:17], v[78:81], v[94:97], v[2:17]
	s_cbranch_vccnz .LBB0_207
	s_andn2_b64 vcc, exec, s[72:73]
	s_cbranch_vccnz .LBB0_188
	s_waitcnt vmcnt(3)
	ds_write_b128 v224, v[114:117]
	s_waitcnt vmcnt(1)
	ds_write_b128 v224, v[122:125] offset:8192
	ds_write_b128 v173, v[118:121]
	s_waitcnt vmcnt(0)
	ds_write_b128 v175, v[126:129]

.LBB0_190:
	ds_read_b128 v[66:69], v225 offset:32768
	ds_read_b128 v[70:73], v226 offset:32768
	ds_read_b128 v[74:77], v227 offset:32768
	ds_read_b128 v[78:81], v228 offset:32768
	ds_read_b128 v[212:215], v225 offset:40960
	ds_read_b128 v[250:253], v226 offset:40960
	s_sub_i32 s8, s98, 64
	s_cmp_le_i32 s8, s74
	s_waitcnt lgkmcnt(5)
	v_mfma_f32_32x32x16_bf16 v[82:97], v[66:69], v[98:101], 0
	s_waitcnt lgkmcnt(4)
	v_mfma_f32_32x32x16_bf16 v[82:97], v[70:73], v[102:105], v[82:97]
	s_waitcnt lgkmcnt(3)
	v_mfma_f32_32x32x16_bf16 v[82:97], v[74:77], v[106:109], v[82:97]
	s_waitcnt lgkmcnt(2)
	v_mfma_f32_32x32x16_bf16 v[82:97], v[78:81], v[110:113], v[82:97]
	s_waitcnt lgkmcnt(1)
	v_mfma_f32_32x32x16_bf16 v[66:81], v[212:215], v[98:101], 0
	ds_read_b128 v[212:215], v227 offset:40960
	s_waitcnt lgkmcnt(1)
	v_mfma_f32_32x32x16_bf16 v[66:81], v[250:253], v[102:105], v[66:81]
	ds_read_b128 v[250:253], v228 offset:40960
	s_waitcnt lgkmcnt(1)
	v_mfma_f32_32x32x16_bf16 v[66:81], v[212:215], v[106:109], v[66:81]
	s_waitcnt lgkmcnt(0)
	v_mfma_f32_32x32x16_bf16 v[66:81], v[250:253], v[110:113], v[66:81]
	s_cbranch_scc1 .LBB0_192
	v_add_u32_e32 v1, 0xffffff80, v231
	v_cmp_gt_i32_e64 s[68:69], 26, v1
	v_cmp_gt_i32_e64 s[70:71], 27, v1
	v_cmp_gt_i32_e64 s[66:67], 25, v1
	s_and_b64 s[68:69], s[70:71], s[68:69]
	v_cmp_gt_i32_e64 s[64:65], 24, v1
	s_and_b64 s[66:67], s[68:69], s[66:67]
	v_cmp_gt_i32_e64 s[62:63], 19, v1
	s_and_b64 s[64:65], s[66:67], s[64:65]
	v_cmp_gt_i32_e64 s[60:61], 18, v1
	s_and_b64 s[62:63], s[64:65], s[62:63]
	v_cmp_gt_i32_e64 s[58:59], 17, v1
	s_and_b64 s[60:61], s[62:63], s[60:61]
	v_cmp_gt_i32_e64 s[56:57], 16, v1
	s_and_b64 s[58:59], s[60:61], s[58:59]
	v_cmp_gt_i32_e64 s[54:55], 11, v1
	s_and_b64 s[56:57], s[58:59], s[56:57]
	v_cmp_gt_i32_e64 s[52:53], 10, v1
	s_and_b64 s[54:55], s[56:57], s[54:55]
	v_cmp_gt_i32_e64 s[50:51], 9, v1
	s_and_b64 s[52:53], s[54:55], s[52:53]
	v_cmp_gt_i32_e64 s[48:49], 8, v1
	s_and_b64 s[50:51], s[52:53], s[50:51]
	v_cmp_gt_i32_e64 s[46:47], 3, v1
	s_and_b64 s[48:49], s[50:51], s[48:49]
	v_cmp_gt_i32_e64 s[44:45], 2, v1
	s_and_b64 s[46:47], s[48:49], s[46:47]
	v_cmp_gt_i32_e64 s[42:43], 1, v1
	s_and_b64 s[44:45], s[46:47], s[44:45]
	v_cmp_gt_i32_e64 s[40:41], 0, v1
	s_and_b64 s[42:43], s[44:45], s[42:43]
	s_and_b64 s[40:41], s[42:43], s[40:41]
	v_cmp_gt_i32_e64 s[36:37], 58, v1
	v_cndmask_b32_e64 v82, v82, v210, s[40:41]
	v_cmp_gt_i32_e64 s[40:41], 59, v1
	v_cmp_gt_i32_e64 s[34:35], 57, v1
	s_and_b64 s[36:37], s[40:41], s[36:37]
	v_cmp_gt_i32_e64 s[30:31], 56, v1
	s_and_b64 s[34:35], s[36:37], s[34:35]
	v_cmp_gt_i32_e64 s[28:29], 51, v1
	s_and_b64 s[30:31], s[34:35], s[30:31]
	v_cmp_gt_i32_e64 s[26:27], 50, v1
	s_and_b64 s[28:29], s[30:31], s[28:29]
	v_cmp_gt_i32_e64 s[24:25], 49, v1
	s_and_b64 s[26:27], s[28:29], s[26:27]
	v_cmp_gt_i32_e64 s[22:23], 48, v1
	s_and_b64 s[24:25], s[26:27], s[24:25]
	v_cmp_gt_i32_e64 s[20:21], 43, v1
	s_and_b64 s[22:23], s[24:25], s[22:23]
	v_cmp_gt_i32_e64 s[18:19], 42, v1
	s_and_b64 s[20:21], s[22:23], s[20:21]
	v_cmp_gt_i32_e64 s[16:17], 41, v1
	s_and_b64 s[18:19], s[20:21], s[18:19]
	v_cmp_gt_i32_e64 s[14:15], 40, v1
	s_and_b64 s[16:17], s[18:19], s[16:17]
	v_cmp_gt_i32_e64 s[12:13], 35, v1
	s_and_b64 s[14:15], s[16:17], s[14:15]
	v_cmp_gt_i32_e64 s[10:11], 34, v1
	s_and_b64 s[12:13], s[14:15], s[12:13]
	v_cmp_gt_i32_e64 s[8:9], 33, v1
	s_and_b64 s[10:11], s[12:13], s[10:11]
	v_cmp_gt_i32_e32 vcc, 32, v1
	s_and_b64 s[8:9], s[10:11], s[8:9]
	s_and_b64 vcc, s[8:9], vcc
	v_cndmask_b32_e64 v97, v97, v210, s[70:71]
	v_cndmask_b32_e64 v96, v96, v210, s[68:69]
	v_cndmask_b32_e64 v95, v95, v210, s[66:67]
	v_cndmask_b32_e64 v94, v94, v210, s[64:65]
	v_cndmask_b32_e64 v93, v93, v210, s[62:63]
	v_cndmask_b32_e64 v92, v92, v210, s[60:61]
	v_cndmask_b32_e64 v91, v91, v210, s[58:59]
	v_cndmask_b32_e64 v90, v90, v210, s[56:57]
	v_cndmask_b32_e64 v89, v89, v210, s[54:55]
	v_cndmask_b32_e64 v88, v88, v210, s[52:53]
	v_cndmask_b32_e64 v87, v87, v210, s[50:51]
	v_cndmask_b32_e64 v86, v86, v210, s[48:49]
	v_cndmask_b32_e64 v85, v85, v210, s[46:47]
	v_cndmask_b32_e64 v84, v84, v210, s[44:45]
	v_cndmask_b32_e64 v83, v83, v210, s[42:43]
	v_cndmask_b32_e64 v81, v81, v210, s[40:41]
	v_cndmask_b32_e64 v80, v80, v210, s[36:37]
	v_cndmask_b32_e64 v79, v79, v210, s[34:35]
	v_cndmask_b32_e64 v78, v78, v210, s[30:31]
	v_cndmask_b32_e64 v77, v77, v210, s[28:29]
	v_cndmask_b32_e64 v76, v76, v210, s[26:27]
	v_cndmask_b32_e64 v75, v75, v210, s[24:25]
	v_cndmask_b32_e64 v74, v74, v210, s[22:23]
	v_cndmask_b32_e64 v73, v73, v210, s[20:21]
	v_cndmask_b32_e64 v72, v72, v210, s[18:19]
	v_cndmask_b32_e64 v71, v71, v210, s[16:17]
	v_cndmask_b32_e64 v70, v70, v210, s[14:15]
	v_cndmask_b32_e64 v69, v69, v210, s[12:13]
	v_cndmask_b32_e64 v68, v68, v210, s[10:11]
	v_cndmask_b32_e64 v67, v67, v210, s[8:9]
	v_cndmask_b32_e32 v66, v66, v210, vcc

.LBB0_196:
	v_cndmask_b32_e64 v233, v234, v233, s[8:9]
	v_mul_f32_e32 v206, 0xbe38aa3b, v233
	v_fmamk_f32 v82, v82, 0x3e38aa3b, v206
	v_fmamk_f32 v83, v83, 0x3e38aa3b, v206
	v_fmamk_f32 v84, v84, 0x3e38aa3b, v206
	v_fmamk_f32 v85, v85, 0x3e38aa3b, v206
	v_fmamk_f32 v86, v86, 0x3e38aa3b, v206
	v_fmamk_f32 v87, v87, 0x3e38aa3b, v206
	v_fmamk_f32 v88, v88, 0x3e38aa3b, v206
	v_fmamk_f32 v89, v89, 0x3e38aa3b, v206
	v_fmamk_f32 v90, v90, 0x3e38aa3b, v206
	v_fmamk_f32 v91, v91, 0x3e38aa3b, v206
	v_fmamk_f32 v92, v92, 0x3e38aa3b, v206
	v_fmamk_f32 v93, v93, 0x3e38aa3b, v206
	v_fmamk_f32 v94, v94, 0x3e38aa3b, v206
	v_fmamk_f32 v95, v95, 0x3e38aa3b, v206
	v_fmamk_f32 v96, v96, 0x3e38aa3b, v206
	v_fmamk_f32 v97, v97, 0x3e38aa3b, v206
	v_fmamk_f32 v66, v66, 0x3e38aa3b, v206
	v_fmamk_f32 v67, v67, 0x3e38aa3b, v206
	v_fmamk_f32 v68, v68, 0x3e38aa3b, v206
	v_fmamk_f32 v69, v69, 0x3e38aa3b, v206
	v_fmamk_f32 v70, v70, 0x3e38aa3b, v206
	v_fmamk_f32 v71, v71, 0x3e38aa3b, v206
	v_fmamk_f32 v72, v72, 0x3e38aa3b, v206
	v_fmamk_f32 v73, v73, 0x3e38aa3b, v206
	v_fmamk_f32 v74, v74, 0x3e38aa3b, v206
	v_fmamk_f32 v75, v75, 0x3e38aa3b, v206
	v_fmamk_f32 v76, v76, 0x3e38aa3b, v206
	v_fmamk_f32 v77, v77, 0x3e38aa3b, v206
	v_fmamk_f32 v78, v78, 0x3e38aa3b, v206
	v_fmamk_f32 v79, v79, 0x3e38aa3b, v206
	v_fmamk_f32 v80, v80, 0x3e38aa3b, v206
	v_fmac_f32_e32 v206, 0x3e38aa3b, v81
	v_exp_f32_e32 v81, v82
	v_exp_f32_e32 v82, v83
	v_exp_f32_e32 v83, v84
	v_exp_f32_e32 v84, v85
	v_exp_f32_e32 v85, v86
	v_exp_f32_e32 v86, v87
	v_exp_f32_e32 v87, v88
	v_exp_f32_e32 v88, v89
	v_exp_f32_e32 v89, v90
	v_exp_f32_e32 v90, v91
	v_exp_f32_e32 v91, v92
	v_exp_f32_e32 v92, v93
	v_exp_f32_e32 v93, v94
	v_exp_f32_e32 v94, v95
	v_exp_f32_e32 v95, v96
	v_exp_f32_e32 v96, v97
	v_exp_f32_e32 v97, v66
	v_add_f32_e32 v66, 0, v81
	v_add_f32_e32 v66, v82, v66
	v_add_f32_e32 v66, v83, v66
	v_add_f32_e32 v66, v84, v66
	v_add_f32_e32 v66, v85, v66
	v_add_f32_e32 v66, v86, v66
	v_add_f32_e32 v66, v87, v66
	v_add_f32_e32 v66, v88, v66
	v_add_f32_e32 v66, v89, v66
	v_add_f32_e32 v66, v90, v66
	v_add_f32_e32 v66, v91, v66
	v_add_f32_e32 v66, v92, v66
	v_add_f32_e32 v66, v93, v66
	v_exp_f32_e32 v212, v67
	v_add_f32_e32 v66, v94, v66
	v_exp_f32_e32 v213, v68
	v_add_f32_e32 v66, v95, v66
	v_exp_f32_e32 v214, v69
	v_add_f32_e32 v66, v96, v66
	v_exp_f32_e32 v215, v70
	v_add_f32_e32 v66, v97, v66
	v_exp_f32_e32 v236, v71
	v_add_f32_e32 v66, v212, v66
	v_exp_f32_e32 v237, v72
	v_add_f32_e32 v66, v213, v66
	v_exp_f32_e32 v238, v73
	v_add_f32_e32 v66, v214, v66
	v_exp_f32_e32 v239, v74
	v_add_f32_e32 v66, v215, v66
	v_exp_f32_e32 v240, v75
	v_add_f32_e32 v66, v236, v66
	v_exp_f32_e32 v241, v76
	v_add_f32_e32 v66, v237, v66
	v_exp_f32_e32 v242, v77
	v_add_f32_e32 v66, v238, v66
	v_exp_f32_e32 v243, v78
	v_add_f32_e32 v66, v239, v66
	v_exp_f32_e32 v244, v79
	v_add_f32_e32 v66, v240, v66
	v_exp_f32_e32 v245, v80
	v_add_f32_e32 v66, v241, v66
	v_exp_f32_e32 v206, v206
	v_add_f32_e32 v66, v242, v66
	v_add_f32_e32 v66, v243, v66
	v_add_f32_e32 v66, v244, v66
	v_add_f32_e32 v66, v245, v66
	v_add_f32_e32 v234, v206, v66
	v_mov_b32_e32 v235, v234
	s_nop 1
	v_permlane32_swap_b32_e32 v234, v235
	v_cvt_pk_bf16_f32 v66, v81, v82
	v_cvt_pk_bf16_f32 v67, v83, v84
	v_cvt_pk_bf16_f32 v68, v85, v86
	v_cvt_pk_bf16_f32 v69, v87, v88
	v_cvt_pk_bf16_f32 v70, v89, v90
	v_cvt_pk_bf16_f32 v71, v91, v92
	v_cvt_pk_bf16_f32 v72, v93, v94
	v_cvt_pk_bf16_f32 v73, v95, v96
	v_cvt_pk_bf16_f32 v74, v97, v212
	v_cvt_pk_bf16_f32 v75, v213, v214
	v_cvt_pk_bf16_f32 v76, v215, v236
	v_cvt_pk_bf16_f32 v77, v237, v238
	v_cvt_pk_bf16_f32 v78, v239, v240
	v_cvt_pk_bf16_f32 v79, v241, v242
	v_cvt_pk_bf16_f32 v80, v243, v244
	v_cvt_pk_bf16_f32 v81, v245, v206
	s_nop 0
	v_permlane32_swap_b32_e32 v66, v68
	v_permlane32_swap_b32_e32 v67, v69
	v_permlane32_swap_b32_e32 v70, v72
	v_permlane32_swap_b32_e32 v71, v73
	v_permlane32_swap_b32_e32 v74, v76
	v_permlane32_swap_b32_e32 v75, v77
	v_permlane32_swap_b32_e32 v78, v80
	v_permlane32_swap_b32_e32 v79, v81
	ds_read_b64_tr_b16 v[82:83], v153 offset:0x8000
	ds_read_b64_tr_b16 v[84:85], v153 offset:0x8800
	ds_read_b64_tr_b16 v[86:87], v153 offset:0x9000
	ds_read_b64_tr_b16 v[88:89], v153 offset:0x9800
	ds_read_b64_tr_b16 v[90:91], v153 offset:0xa000
	ds_read_b64_tr_b16 v[92:93], v153 offset:0xa800
	ds_read_b64_tr_b16 v[94:95], v153 offset:0xb000
	ds_read_b64_tr_b16 v[96:97], v153 offset:0xb800
	s_nop 0
	s_waitcnt lgkmcnt(6)
	v_mfma_f32_32x32x16_bf16 v[50:65], v[66:69], v[82:85], v[50:65]
	ds_read_b64_tr_b16 v[82:83], v153 offset:0x8200
	ds_read_b64_tr_b16 v[84:85], v153 offset:0x8a00
	s_waitcnt lgkmcnt(6)
	v_mfma_f32_32x32x16_bf16 v[50:65], v[70:73], v[86:89], v[50:65]
	ds_read_b64_tr_b16 v[86:87], v153 offset:0x9200
	ds_read_b64_tr_b16 v[88:89], v153 offset:0x9a00
	s_waitcnt lgkmcnt(6)
	v_mfma_f32_32x32x16_bf16 v[50:65], v[74:77], v[90:93], v[50:65]
	ds_read_b64_tr_b16 v[90:91], v153 offset:0xa200
	ds_read_b64_tr_b16 v[92:93], v153 offset:0xaa00
	s_waitcnt lgkmcnt(6)
	v_mfma_f32_32x32x16_bf16 v[50:65], v[78:81], v[94:97], v[50:65]
	ds_read_b64_tr_b16 v[94:95], v153 offset:0xb200
	ds_read_b64_tr_b16 v[96:97], v153 offset:0xba00
	s_waitcnt lgkmcnt(6)
	v_mfma_f32_32x32x16_bf16 v[34:49], v[66:69], v[82:85], v[34:49]
	ds_read_b64_tr_b16 v[82:83], v153 offset:0x8400
	ds_read_b64_tr_b16 v[84:85], v153 offset:0x8c00
	s_waitcnt lgkmcnt(6)
	v_mfma_f32_32x32x16_bf16 v[34:49], v[70:73], v[86:89], v[34:49]
	ds_read_b64_tr_b16 v[86:87], v153 offset:0x9400
	ds_read_b64_tr_b16 v[88:89], v153 offset:0x9c00
	s_waitcnt lgkmcnt(6)
	v_mfma_f32_32x32x16_bf16 v[34:49], v[74:77], v[90:93], v[34:49]
	ds_read_b64_tr_b16 v[90:91], v153 offset:0xa400
	ds_read_b64_tr_b16 v[92:93], v153 offset:0xac00
	s_waitcnt lgkmcnt(6)
	v_mfma_f32_32x32x16_bf16 v[34:49], v[78:81], v[94:97], v[34:49]
	ds_read_b64_tr_b16 v[94:95], v153 offset:0xb400
	ds_read_b64_tr_b16 v[96:97], v153 offset:0xbc00
	s_waitcnt lgkmcnt(6)
	v_mfma_f32_32x32x16_bf16 v[18:33], v[66:69], v[82:85], v[18:33]
	ds_read_b64_tr_b16 v[82:83], v153 offset:0x8600
	ds_read_b64_tr_b16 v[84:85], v153 offset:0x8e00
	s_waitcnt lgkmcnt(6)
	v_mfma_f32_32x32x16_bf16 v[18:33], v[70:73], v[86:89], v[18:33]
	ds_read_b64_tr_b16 v[86:87], v153 offset:0x9600
	ds_read_b64_tr_b16 v[88:89], v153 offset:0x9e00
	s_waitcnt lgkmcnt(6)
	v_mfma_f32_32x32x16_bf16 v[18:33], v[74:77], v[90:93], v[18:33]
	ds_read_b64_tr_b16 v[90:91], v153 offset:0xa600
	ds_read_b64_tr_b16 v[92:93], v153 offset:0xae00
	s_waitcnt lgkmcnt(6)
	v_mfma_f32_32x32x16_bf16 v[18:33], v[78:81], v[94:97], v[18:33]
	ds_read_b64_tr_b16 v[94:95], v153 offset:0xb600
	ds_read_b64_tr_b16 v[96:97], v153 offset:0xbe00
	s_waitcnt lgkmcnt(6)
	v_mfma_f32_32x32x16_bf16 v[2:17], v[66:69], v[82:85], v[2:17]
	s_andn2_b64 vcc, exec, s[38:39]
	s_waitcnt lgkmcnt(4)
	v_mfma_f32_32x32x16_bf16 v[2:17], v[70:73], v[86:89], v[2:17]
	s_waitcnt lgkmcnt(2)
	v_mfma_f32_32x32x16_bf16 v[2:17], v[74:77], v[90:93], v[2:17]
	s_waitcnt lgkmcnt(0)
	v_mfma_f32_32x32x16_bf16 v[2:17], v[78:81], v[94:97], v[2:17]
	s_cbranch_vccnz .LBB0_198
	s_waitcnt vmcnt(3)
	ds_write_b128 v224, v[114:117] offset:16384
	s_waitcnt vmcnt(1)
	ds_write_b128 v224, v[122:125] offset:24576
	ds_write_b128 v229, v[118:121]
	s_waitcnt vmcnt(0)
	ds_write_b128 v230, v[126:129]

.LBB0_200:
	ds_read_b128 v[66:69], v225 offset:49152
	ds_read_b128 v[70:73], v226 offset:49152
	ds_read_b128 v[74:77], v227 offset:49152
	ds_read_b128 v[78:81], v228 offset:49152
	ds_read_b128 v[212:215], v225 offset:57344
	ds_read_b128 v[250:253], v226 offset:57344
	s_cmp_le_i32 s98, s74
	s_waitcnt lgkmcnt(5)
	v_mfma_f32_32x32x16_bf16 v[82:97], v[66:69], v[98:101], 0
	s_waitcnt lgkmcnt(4)
	v_mfma_f32_32x32x16_bf16 v[82:97], v[70:73], v[102:105], v[82:97]
	s_waitcnt lgkmcnt(3)
	v_mfma_f32_32x32x16_bf16 v[82:97], v[74:77], v[106:109], v[82:97]
	s_waitcnt lgkmcnt(2)
	v_mfma_f32_32x32x16_bf16 v[82:97], v[78:81], v[110:113], v[82:97]
	s_waitcnt lgkmcnt(1)
	v_mfma_f32_32x32x16_bf16 v[66:81], v[212:215], v[98:101], 0
	ds_read_b128 v[212:215], v227 offset:57344
	s_waitcnt lgkmcnt(1)
	v_mfma_f32_32x32x16_bf16 v[66:81], v[250:253], v[102:105], v[66:81]
	ds_read_b128 v[250:253], v228 offset:57344
	s_waitcnt lgkmcnt(1)
	v_mfma_f32_32x32x16_bf16 v[66:81], v[212:215], v[106:109], v[66:81]
	s_waitcnt lgkmcnt(0)
	v_mfma_f32_32x32x16_bf16 v[66:81], v[250:253], v[110:113], v[66:81]
	s_cbranch_scc1 .LBB0_202
	v_add_u32_e32 v206, 0xffffff40, v231
	v_cmp_gt_i32_e64 s[68:69], 26, v206
	v_cmp_gt_i32_e64 s[70:71], 27, v206
	v_cmp_gt_i32_e64 s[66:67], 25, v206
	s_and_b64 s[68:69], s[70:71], s[68:69]
	v_cmp_gt_i32_e64 s[64:65], 24, v206
	s_and_b64 s[66:67], s[68:69], s[66:67]
	v_cmp_gt_i32_e64 s[62:63], 19, v206
	s_and_b64 s[64:65], s[66:67], s[64:65]
	v_cmp_gt_i32_e64 s[60:61], 18, v206
	s_and_b64 s[62:63], s[64:65], s[62:63]
	v_cmp_gt_i32_e64 s[58:59], 17, v206
	s_and_b64 s[60:61], s[62:63], s[60:61]
	v_cmp_gt_i32_e64 s[56:57], 16, v206
	s_and_b64 s[58:59], s[60:61], s[58:59]
	v_cmp_gt_i32_e64 s[54:55], 11, v206
	s_and_b64 s[56:57], s[58:59], s[56:57]
	v_cmp_gt_i32_e64 s[52:53], 10, v206
	s_and_b64 s[54:55], s[56:57], s[54:55]
	v_cmp_gt_i32_e64 s[50:51], 9, v206
	s_and_b64 s[52:53], s[54:55], s[52:53]
	v_cmp_gt_i32_e64 s[48:49], 8, v206
	s_and_b64 s[50:51], s[52:53], s[50:51]
	v_cmp_gt_i32_e64 s[46:47], 3, v206
	s_and_b64 s[48:49], s[50:51], s[48:49]
	v_cmp_gt_i32_e64 s[44:45], 2, v206
	s_and_b64 s[46:47], s[48:49], s[46:47]
	v_cmp_gt_i32_e64 s[42:43], 1, v206
	s_and_b64 s[44:45], s[46:47], s[44:45]
	v_cmp_gt_i32_e64 s[40:41], 0, v206
	s_and_b64 s[42:43], s[44:45], s[42:43]
	s_and_b64 s[40:41], s[42:43], s[40:41]
	v_cmp_gt_i32_e64 s[36:37], 58, v206
	v_cndmask_b32_e64 v82, v82, v210, s[40:41]
	v_cmp_gt_i32_e64 s[40:41], 59, v206
	v_cmp_gt_i32_e64 s[34:35], 57, v206
	s_and_b64 s[36:37], s[40:41], s[36:37]
	v_cmp_gt_i32_e64 s[30:31], 56, v206
	s_and_b64 s[34:35], s[36:37], s[34:35]
	v_cmp_gt_i32_e64 s[28:29], 51, v206
	s_and_b64 s[30:31], s[34:35], s[30:31]
	v_cmp_gt_i32_e64 s[26:27], 50, v206
	s_and_b64 s[28:29], s[30:31], s[28:29]
	v_cmp_gt_i32_e64 s[24:25], 49, v206
	s_and_b64 s[26:27], s[28:29], s[26:27]
	v_cmp_gt_i32_e64 s[22:23], 48, v206
	s_and_b64 s[24:25], s[26:27], s[24:25]
	v_cmp_gt_i32_e64 s[20:21], 43, v206
	s_and_b64 s[22:23], s[24:25], s[22:23]
	v_cmp_gt_i32_e64 s[18:19], 42, v206
	s_and_b64 s[20:21], s[22:23], s[20:21]
	v_cmp_gt_i32_e64 s[16:17], 41, v206
	s_and_b64 s[18:19], s[20:21], s[18:19]
	v_cmp_gt_i32_e64 s[14:15], 40, v206
	s_and_b64 s[16:17], s[18:19], s[16:17]
	v_cmp_gt_i32_e64 s[12:13], 35, v206
	s_and_b64 s[14:15], s[16:17], s[14:15]
	v_cmp_gt_i32_e64 s[10:11], 34, v206
	s_and_b64 s[12:13], s[14:15], s[12:13]
	v_cmp_gt_i32_e64 s[8:9], 33, v206
	s_and_b64 s[10:11], s[12:13], s[10:11]
	v_cmp_gt_i32_e32 vcc, 32, v206
	s_and_b64 s[8:9], s[10:11], s[8:9]
	s_and_b64 vcc, s[8:9], vcc
	v_cndmask_b32_e64 v97, v97, v210, s[70:71]
	v_cndmask_b32_e64 v96, v96, v210, s[68:69]
	v_cndmask_b32_e64 v95, v95, v210, s[66:67]
	v_cndmask_b32_e64 v94, v94, v210, s[64:65]
	v_cndmask_b32_e64 v93, v93, v210, s[62:63]
	v_cndmask_b32_e64 v92, v92, v210, s[60:61]
	v_cndmask_b32_e64 v91, v91, v210, s[58:59]
	v_cndmask_b32_e64 v90, v90, v210, s[56:57]
	v_cndmask_b32_e64 v89, v89, v210, s[54:55]
	v_cndmask_b32_e64 v88, v88, v210, s[52:53]
	v_cndmask_b32_e64 v87, v87, v210, s[50:51]
	v_cndmask_b32_e64 v86, v86, v210, s[48:49]
	v_cndmask_b32_e64 v85, v85, v210, s[46:47]
	v_cndmask_b32_e64 v84, v84, v210, s[44:45]
	v_cndmask_b32_e64 v83, v83, v210, s[42:43]
	v_cndmask_b32_e64 v81, v81, v210, s[40:41]
	v_cndmask_b32_e64 v80, v80, v210, s[36:37]
	v_cndmask_b32_e64 v79, v79, v210, s[34:35]
	v_cndmask_b32_e64 v78, v78, v210, s[30:31]
	v_cndmask_b32_e64 v77, v77, v210, s[28:29]
	v_cndmask_b32_e64 v76, v76, v210, s[26:27]
	v_cndmask_b32_e64 v75, v75, v210, s[24:25]
	v_cndmask_b32_e64 v74, v74, v210, s[22:23]
	v_cndmask_b32_e64 v73, v73, v210, s[20:21]
	v_cndmask_b32_e64 v72, v72, v210, s[18:19]
	v_cndmask_b32_e64 v71, v71, v210, s[16:17]
	v_cndmask_b32_e64 v70, v70, v210, s[14:15]
	v_cndmask_b32_e64 v69, v69, v210, s[12:13]
	v_cndmask_b32_e64 v68, v68, v210, s[10:11]
	v_cndmask_b32_e64 v67, v67, v210, s[8:9]
	v_cndmask_b32_e32 v66, v66, v210, vcc

.LBB0_206:
	v_cndmask_b32_e64 v233, v237, v233, s[8:9]
	v_mul_f32_e32 v206, 0xbe38aa3b, v233
	v_fmamk_f32 v82, v82, 0x3e38aa3b, v206
	v_fmamk_f32 v83, v83, 0x3e38aa3b, v206
	v_fmamk_f32 v84, v84, 0x3e38aa3b, v206
	v_fmamk_f32 v85, v85, 0x3e38aa3b, v206
	v_fmamk_f32 v86, v86, 0x3e38aa3b, v206
	v_fmamk_f32 v87, v87, 0x3e38aa3b, v206
	v_fmamk_f32 v88, v88, 0x3e38aa3b, v206
	v_fmamk_f32 v89, v89, 0x3e38aa3b, v206
	v_fmamk_f32 v90, v90, 0x3e38aa3b, v206
	v_fmamk_f32 v91, v91, 0x3e38aa3b, v206
	v_fmamk_f32 v92, v92, 0x3e38aa3b, v206
	v_fmamk_f32 v93, v93, 0x3e38aa3b, v206
	v_fmamk_f32 v94, v94, 0x3e38aa3b, v206
	v_fmamk_f32 v95, v95, 0x3e38aa3b, v206
	v_fmamk_f32 v96, v96, 0x3e38aa3b, v206
	v_fmamk_f32 v97, v97, 0x3e38aa3b, v206
	v_fmamk_f32 v66, v66, 0x3e38aa3b, v206
	v_fmamk_f32 v67, v67, 0x3e38aa3b, v206
	v_fmamk_f32 v68, v68, 0x3e38aa3b, v206
	v_fmamk_f32 v69, v69, 0x3e38aa3b, v206
	v_fmamk_f32 v70, v70, 0x3e38aa3b, v206
	v_fmamk_f32 v71, v71, 0x3e38aa3b, v206
	v_fmamk_f32 v72, v72, 0x3e38aa3b, v206
	v_fmamk_f32 v73, v73, 0x3e38aa3b, v206
	v_fmamk_f32 v74, v74, 0x3e38aa3b, v206
	v_fmamk_f32 v75, v75, 0x3e38aa3b, v206
	v_fmamk_f32 v76, v76, 0x3e38aa3b, v206
	v_fmamk_f32 v77, v77, 0x3e38aa3b, v206
	v_fmamk_f32 v78, v78, 0x3e38aa3b, v206
	v_fmamk_f32 v79, v79, 0x3e38aa3b, v206
	v_fmamk_f32 v80, v80, 0x3e38aa3b, v206
	v_fmac_f32_e32 v206, 0x3e38aa3b, v81
	v_exp_f32_e32 v81, v82
	v_exp_f32_e32 v82, v83
	v_exp_f32_e32 v83, v84
	v_exp_f32_e32 v84, v85
	v_exp_f32_e32 v85, v86
	v_exp_f32_e32 v86, v87
	v_exp_f32_e32 v87, v88
	v_exp_f32_e32 v88, v89
	v_exp_f32_e32 v89, v90
	v_exp_f32_e32 v90, v91
	v_exp_f32_e32 v91, v92
	v_exp_f32_e32 v92, v93
	v_exp_f32_e32 v93, v94
	v_exp_f32_e32 v94, v95
	v_exp_f32_e32 v95, v96
	v_exp_f32_e32 v96, v97
	v_add_f32_e32 v97, v234, v235
	v_fmac_f32_e32 v97, v232, v1
	v_exp_f32_e32 v1, v66
	v_add_f32_e32 v66, 0, v81
	v_add_f32_e32 v66, v82, v66
	v_add_f32_e32 v66, v83, v66
	v_add_f32_e32 v66, v84, v66
	v_add_f32_e32 v66, v85, v66
	v_add_f32_e32 v66, v86, v66
	v_add_f32_e32 v66, v87, v66
	v_add_f32_e32 v66, v88, v66
	v_add_f32_e32 v66, v89, v66
	v_add_f32_e32 v66, v90, v66
	v_add_f32_e32 v66, v91, v66
	v_add_f32_e32 v66, v92, v66
	v_add_f32_e32 v66, v93, v66
	v_exp_f32_e32 v212, v67
	v_add_f32_e32 v66, v94, v66
	v_exp_f32_e32 v213, v68
	v_add_f32_e32 v66, v95, v66
	v_exp_f32_e32 v214, v69
	v_add_f32_e32 v66, v96, v66
	v_exp_f32_e32 v215, v70
	v_add_f32_e32 v66, v1, v66
	v_exp_f32_e32 v234, v71
	v_add_f32_e32 v66, v212, v66
	v_exp_f32_e32 v235, v72
	v_add_f32_e32 v66, v213, v66
	v_exp_f32_e32 v237, v73
	v_add_f32_e32 v66, v214, v66
	v_exp_f32_e32 v238, v74
	v_add_f32_e32 v66, v215, v66
	v_exp_f32_e32 v239, v75
	v_add_f32_e32 v66, v234, v66
	v_exp_f32_e32 v240, v76
	v_add_f32_e32 v66, v235, v66
	v_exp_f32_e32 v241, v77
	v_add_f32_e32 v66, v237, v66
	v_exp_f32_e32 v242, v78
	v_add_f32_e32 v66, v238, v66
	v_exp_f32_e32 v243, v79
	v_add_f32_e32 v66, v239, v66
	v_exp_f32_e32 v244, v80
	v_add_f32_e32 v66, v240, v66
	v_exp_f32_e32 v206, v206
	v_add_f32_e32 v66, v241, v66
	v_add_f32_e32 v66, v242, v66
	v_add_f32_e32 v66, v243, v66
	v_add_f32_e32 v66, v244, v66
	v_add_f32_e32 v66, v206, v66
	v_mov_b32_e32 v67, v66
	s_nop 1
	v_permlane32_swap_b32_e32 v66, v67
	v_add_f32_e32 v232, v66, v67
	v_fmac_f32_e32 v232, v97, v236
	v_cvt_pk_bf16_f32 v66, v81, v82
	v_cvt_pk_bf16_f32 v67, v83, v84
	v_cvt_pk_bf16_f32 v68, v85, v86
	v_cvt_pk_bf16_f32 v69, v87, v88
	v_cvt_pk_bf16_f32 v70, v89, v90
	v_cvt_pk_bf16_f32 v71, v91, v92
	v_cvt_pk_bf16_f32 v72, v93, v94
	v_cvt_pk_bf16_f32 v73, v95, v96
	v_cvt_pk_bf16_f32 v74, v1, v212
	v_cvt_pk_bf16_f32 v75, v213, v214
	v_cvt_pk_bf16_f32 v76, v215, v234
	v_cvt_pk_bf16_f32 v77, v235, v237
	v_cvt_pk_bf16_f32 v78, v238, v239
	v_cvt_pk_bf16_f32 v79, v240, v241
	v_cvt_pk_bf16_f32 v80, v242, v243
	v_cvt_pk_bf16_f32 v81, v244, v206
	s_nop 0
	v_permlane32_swap_b32_e32 v66, v68
	v_permlane32_swap_b32_e32 v67, v69
	v_permlane32_swap_b32_e32 v70, v72
	v_permlane32_swap_b32_e32 v71, v73
	v_permlane32_swap_b32_e32 v74, v76
	v_permlane32_swap_b32_e32 v75, v77
	v_permlane32_swap_b32_e32 v78, v80
	v_permlane32_swap_b32_e32 v79, v81
	ds_read_b64_tr_b16 v[82:83], v153 offset:0xc000
	ds_read_b64_tr_b16 v[84:85], v153 offset:0xc800
	ds_read_b64_tr_b16 v[86:87], v153 offset:0xd000
	ds_read_b64_tr_b16 v[88:89], v153 offset:0xd800
	ds_read_b64_tr_b16 v[90:91], v153 offset:0xe000
	ds_read_b64_tr_b16 v[92:93], v153 offset:0xe800
	ds_read_b64_tr_b16 v[94:95], v153 offset:0xf000
	ds_read_b64_tr_b16 v[96:97], v153 offset:0xf800
	s_nop 0
	s_waitcnt lgkmcnt(6)
	v_mfma_f32_32x32x16_bf16 v[50:65], v[66:69], v[82:85], v[50:65]
	ds_read_b64_tr_b16 v[82:83], v153 offset:0xc200
	ds_read_b64_tr_b16 v[84:85], v153 offset:0xca00
	s_waitcnt lgkmcnt(6)
	v_mfma_f32_32x32x16_bf16 v[50:65], v[70:73], v[86:89], v[50:65]
	ds_read_b64_tr_b16 v[86:87], v153 offset:0xd200
	ds_read_b64_tr_b16 v[88:89], v153 offset:0xda00
	s_waitcnt lgkmcnt(6)
	v_mfma_f32_32x32x16_bf16 v[50:65], v[74:77], v[90:93], v[50:65]
	ds_read_b64_tr_b16 v[90:91], v153 offset:0xe200
	ds_read_b64_tr_b16 v[92:93], v153 offset:0xea00
	s_waitcnt lgkmcnt(6)
	v_mfma_f32_32x32x16_bf16 v[50:65], v[78:81], v[94:97], v[50:65]
	ds_read_b64_tr_b16 v[94:95], v153 offset:0xf200
	ds_read_b64_tr_b16 v[96:97], v153 offset:0xfa00
	s_waitcnt lgkmcnt(6)
	v_mfma_f32_32x32x16_bf16 v[34:49], v[66:69], v[82:85], v[34:49]
	ds_read_b64_tr_b16 v[82:83], v153 offset:0xc400
	ds_read_b64_tr_b16 v[84:85], v153 offset:0xcc00
	s_waitcnt lgkmcnt(6)
	v_mfma_f32_32x32x16_bf16 v[34:49], v[70:73], v[86:89], v[34:49]
	ds_read_b64_tr_b16 v[86:87], v153 offset:0xd400
	ds_read_b64_tr_b16 v[88:89], v153 offset:0xdc00
	s_waitcnt lgkmcnt(6)
	v_mfma_f32_32x32x16_bf16 v[34:49], v[74:77], v[90:93], v[34:49]
	ds_read_b64_tr_b16 v[90:91], v153 offset:0xe400
	ds_read_b64_tr_b16 v[92:93], v153 offset:0xec00
	s_waitcnt lgkmcnt(6)
	v_mfma_f32_32x32x16_bf16 v[34:49], v[78:81], v[94:97], v[34:49]
	ds_read_b64_tr_b16 v[94:95], v153 offset:0xf400
	ds_read_b64_tr_b16 v[96:97], v153 offset:0xfc00
	s_waitcnt lgkmcnt(6)
	v_mfma_f32_32x32x16_bf16 v[18:33], v[66:69], v[82:85], v[18:33]
	ds_read_b64_tr_b16 v[82:83], v153 offset:0xc600
	ds_read_b64_tr_b16 v[84:85], v153 offset:0xce00
	s_waitcnt lgkmcnt(6)
	v_mfma_f32_32x32x16_bf16 v[18:33], v[70:73], v[86:89], v[18:33]
	ds_read_b64_tr_b16 v[86:87], v153 offset:0xd600
	ds_read_b64_tr_b16 v[88:89], v153 offset:0xde00
	s_waitcnt lgkmcnt(6)
	v_mfma_f32_32x32x16_bf16 v[18:33], v[74:77], v[90:93], v[18:33]
	ds_read_b64_tr_b16 v[90:91], v153 offset:0xe600
	ds_read_b64_tr_b16 v[92:93], v153 offset:0xee00
	s_waitcnt lgkmcnt(6)
	v_mfma_f32_32x32x16_bf16 v[18:33], v[78:81], v[94:97], v[18:33]
	ds_read_b64_tr_b16 v[94:95], v153 offset:0xf600
	ds_read_b64_tr_b16 v[96:97], v153 offset:0xfe00
	s_waitcnt lgkmcnt(6)
	v_mfma_f32_32x32x16_bf16 v[2:17], v[66:69], v[82:85], v[2:17]
	s_waitcnt lgkmcnt(0)
	s_barrier
	s_waitcnt lgkmcnt(4)
	v_mfma_f32_32x32x16_bf16 v[2:17], v[70:73], v[86:89], v[2:17]
	s_waitcnt lgkmcnt(2)
	v_mfma_f32_32x32x16_bf16 v[2:17], v[74:77], v[90:93], v[2:17]
	s_waitcnt lgkmcnt(0)
	v_mfma_f32_32x32x16_bf16 v[2:17], v[78:81], v[94:97], v[2:17]
